# saddr-form loads also in the phase-11 k-loop (same conversion as phases 6 and 13)
# baseline (speedup 1.0000x reference)
.LBB0_2271:
	s_lshr_b32 s6, s26, 3
	s_and_b32 s6, s6, 24
	s_add_i32 s7, s3, s6
	s_and_b32 s10, s2, 7
	s_add_i32 s7, s7, s10
	s_lshl_b32 s10, s7, 18
	s_lshl_b32 s7, s6, 3
	s_sub_i32 s7, s26, s7
	s_ashr_i32 s14, s7, 3
	s_and_b32 s7, s26, 7
	s_or_b32 s7, s7, s3
	s_or_b32 s27, s7, s6
	v_lshl_add_u64 v[138:139], v[122:123], 0, s[10:11]
	v_lshl_add_u64 v[140:141], v[124:125], 0, s[10:11]
	v_lshl_add_u64 v[142:143], v[126:127], 0, s[10:11]
	v_lshl_add_u64 v[144:145], v[128:129], 0, s[10:11]
	s_ashr_i32 s15, s14, 31
	s_lshl_b32 s10, s27, 18
	s_lshl_b64 s[6:7], s[14:15], 18
	v_lshl_add_u64 v[6:7], v[118:119], 0, s[10:11]
	v_lshl_add_u64 v[4:5], v[116:117], 0, s[6:7]
	v_lshl_add_u64 v[2:3], v[6:7], 0, v[130:131]
	s_waitcnt vmcnt(63) expcnt(7) lgkmcnt(15)
	s_barrier
	s_waitcnt lgkmcnt(0)
	global_load_dwordx4 v[8:11], v[2:3], off
	global_load_dwordx4 v[12:15], v[4:5], off
	v_lshl_add_u64 v[2:3], v[6:7], 0, v[132:133]
	v_add_co_u32_e32 v32, vcc, s21, v4
	v_lshl_add_u64 v[34:35], v[6:7], 0, v[134:135]
	s_nop 0
	v_addc_co_u32_e32 v33, vcc, 0, v5, vcc
	global_load_dwordx4 v[16:19], v[2:3], off
	global_load_dwordx4 v[20:23], v[34:35], off
	global_load_dwordx4 v[24:27], v[32:33], off offset:-4096
	global_load_dwordx4 v[28:31], v[32:33], off
	v_add_co_u32_e32 v40, vcc, s22, v4
	v_lshl_add_u64 v[2:3], v[6:7], 0, v[136:137]
	s_nop 0
	v_addc_co_u32_e32 v41, vcc, 0, v5, vcc
	v_add_co_u32_e32 v46, vcc, s23, v4
	v_lshl_add_u64 v[6:7], v[6:7], 0, s[12:13]
	s_nop 0
	v_addc_co_u32_e32 v47, vcc, 0, v5, vcc
	global_load_dwordx4 v[32:35], v[2:3], off
	v_lshl_add_u64 v[42:43], v[6:7], 0, v[130:131]
	v_lshl_add_u64 v[44:45], v[6:7], 0, v[132:133]
	v_lshl_add_u64 v[48:49], v[6:7], 0, v[134:135]
	v_lshl_add_u64 v[6:7], v[6:7], 0, v[136:137]
	v_add_co_u32_e32 v4, vcc, 0x7000, v4
	global_load_dwordx4 v[36:39], v[40:41], off offset:-4096
	global_load_dwordx4 v[90:93], v[42:43], off
	global_load_dwordx4 v[94:97], v[40:41], off
	global_load_dwordx4 v[82:85], v[44:45], off
	global_load_dwordx4 v[70:73], v[48:49], off
	global_load_dwordx4 v[86:89], v[46:47], off offset:-4096
	global_load_dwordx4 v[74:77], v[46:47], off
	v_addc_co_u32_e32 v5, vcc, 0, v5, vcc
	global_load_dwordx4 v[66:69], v[6:7], off
	global_load_dwordx4 v[78:81], v[4:5], off
	s_mov_b64 s[16:17], 0
	s_mov_b32 s10, 0
	v_mov_b32_e32 v2, v115
	v_mov_b32_e32 v3, v115
	v_mov_b32_e32 v4, v115
	v_mov_b32_e32 v5, v115
	v_mov_b32_e32 v6, v115
	v_lshl_add_u64 v[146:147], v[120:121], 0, s[6:7]
	v_mov_b32_e32 v7, v115
	v_mov_b32_e32 v40, v115
	v_mov_b32_e32 v41, v115
	v_mov_b32_e32 v42, v115
	v_mov_b32_e32 v43, v115
	v_mov_b32_e32 v44, v115
	v_mov_b32_e32 v45, v115
	v_mov_b32_e32 v46, v115
	v_mov_b32_e32 v47, v115
	v_mov_b32_e32 v48, v115
	v_mov_b32_e32 v49, v115
	v_mov_b32_e32 v50, v115
	v_mov_b32_e32 v51, v115
	v_mov_b32_e32 v52, v115
	v_mov_b32_e32 v53, v115
	v_mov_b32_e32 v54, v115
	v_mov_b32_e32 v55, v115
	v_mov_b32_e32 v56, v115
	v_mov_b32_e32 v57, v115
	v_mov_b32_e32 v58, v115
	v_mov_b32_e32 v59, v115
	v_mov_b32_e32 v60, v115
	v_mov_b32_e32 v61, v115
	v_mov_b32_e32 v62, v115
	v_mov_b32_e32 v63, v115
	v_mov_b32_e32 v64, v115
	v_mov_b32_e32 v65, v115
	s_waitcnt vmcnt(15)
	ds_write_b128 v150, v[8:11]
	s_waitcnt vmcnt(14)
	ds_write_b128 v150, v[12:15] offset:18432
	s_waitcnt vmcnt(13)
	ds_write_b128 v152, v[16:19]
	s_waitcnt vmcnt(11)
	ds_write_b128 v152, v[24:27] offset:18432
	ds_write_b128 v154, v[20:23]
	s_waitcnt vmcnt(10)
	ds_write_b128 v154, v[28:31] offset:18432
	s_waitcnt vmcnt(9)
	ds_write_b128 v156, v[32:35]
	s_waitcnt vmcnt(8)
	ds_write_b128 v156, v[36:39] offset:18432
	s_waitcnt lgkmcnt(0)
	s_barrier
	ds_read_b128 v[98:101], v171 offset:4608
	ds_read_b128 v[110:113], v171
	ds_read_b128 v[102:105], v172 offset:23040
	ds_read_b128 v[106:109], v172 offset:18432
	v_mov_b32_e32 v8, v115
	v_mov_b32_e32 v9, v115
	v_mov_b32_e32 v10, v115
	v_mov_b32_e32 v11, v115
	v_mov_b32_e32 v12, v115
	v_mov_b32_e32 v13, v115
	v_mov_b32_e32 v14, v115
	v_mov_b32_e32 v15, v115
	v_mov_b32_e32 v16, v115
	v_mov_b32_e32 v17, v115
	v_mov_b32_e32 v18, v115
	v_mov_b32_e32 v19, v115
	v_mov_b32_e32 v20, v115
	v_mov_b32_e32 v21, v115
	v_mov_b32_e32 v22, v115
	v_mov_b32_e32 v23, v115
	v_mov_b32_e32 v24, v115
	v_mov_b32_e32 v25, v115
	v_mov_b32_e32 v26, v115
	v_mov_b32_e32 v27, v115
	v_mov_b32_e32 v28, v115
	v_mov_b32_e32 v29, v115
	v_mov_b32_e32 v30, v115
	v_mov_b32_e32 v31, v115
	v_mov_b32_e32 v32, v115
	v_mov_b32_e32 v33, v115
	v_mov_b32_e32 v34, v115
	v_mov_b32_e32 v35, v115
	v_mov_b32_e32 v36, v115
	v_mov_b32_e32 v37, v115
	v_mov_b32_e32 v38, v115
	v_mov_b32_e32 v39, v115
	v_subrev_u32_e32 v240, s34, v138
	v_subrev_u32_e32 v241, s34, v140
	v_subrev_u32_e32 v242, s34, v142
	v_subrev_u32_e32 v243, s34, v144
	v_subrev_u32_e32 v244, s34, v146
.LBB0_2272:
	s_add_u32 s62, s34, s16
	s_addc_u32 s63, s35, s17
	s_add_u32 s64, s62, s24
	s_addc_u32 s65, s63, 0
	s_add_u32 s76, s62, s25
	s_addc_u32 s77, s63, 0
	s_and_b32 s6, s10, 1
	s_xor_b32 s7, s6, 1
	s_mul_i32 s15, s7, 0x9000
	v_lshl_or_b32 v173, v148, 1, s15
	v_lshl_add_u32 v178, v149, 1, v173
	s_waitcnt lgkmcnt(0)
	v_mfma_f32_32x32x16_bf16 v[50:65], v[106:109], v[110:113], v[50:65]
	s_waitcnt vmcnt(7)
	ds_write_b128 v178, v[90:93]
	v_lshl_add_u32 v90, v151, 1, v173
	s_waitcnt vmcnt(6)
	ds_write_b128 v178, v[94:97] offset:18432
	s_mul_i32 s6, s6, 0x9000
	v_mfma_f32_32x32x16_bf16 v[34:49], v[102:105], v[110:113], v[34:49]
	s_waitcnt vmcnt(5)
	ds_write_b128 v90, v[82:85]
	v_lshl_add_u32 v82, v153, 1, v173
	v_lshl_add_u32 v83, v155, 1, v173
	s_waitcnt vmcnt(3)
	ds_write_b128 v90, v[86:89] offset:18432
	v_mfma_f32_32x32x16_bf16 v[18:33], v[106:109], v[98:101], v[18:33]
	v_add3_u32 v106, s6, v157, v159
	s_waitcnt vmcnt(1)
	ds_write_b128 v82, v[70:73]
	s_waitcnt vmcnt(2)
	ds_write_b128 v82, v[74:77] offset:18432
	v_add3_u32 v107, s6, v158, v159
	v_mfma_f32_32x32x16_bf16 v[2:17], v[102:105], v[98:101], v[2:17]
	s_waitcnt vmcnt(0)
	ds_write_b128 v83, v[66:69]
	s_waitcnt vmcnt(0)
	ds_write_b128 v83, v[78:81] offset:18432
	ds_read_b128 v[66:69], v106 offset:23072
	ds_read_b128 v[70:73], v107 offset:4640
	global_load_dwordx4 v[90:93], v240, s[62:63]
	s_waitcnt lgkmcnt(0)
	v_mfma_f32_32x32x16_bf16 v[2:17], v[66:69], v[70:73], v[2:17]
	ds_read_b128 v[74:77], v106 offset:18464
	ds_read_b128 v[98:101], v106 offset:18496
	global_load_dwordx4 v[94:97], v244, s[64:65] offset:-4096
	global_load_dwordx4 v[82:85], v241, s[62:63]
	global_load_dwordx4 v[86:89], v244, s[64:65]
	s_waitcnt lgkmcnt(1)
	v_mfma_f32_32x32x16_bf16 v[18:33], v[74:77], v[70:73], v[18:33]
	ds_read_b128 v[70:73], v107 offset:32
	ds_read_b128 v[102:105], v107 offset:64
	v_or_b32_e32 v108, s15, v159
	v_add_u32_e32 v173, v108, v158
	s_add_i32 s10, s10, 1
	s_add_u32 s16, s16, 0x4000
	s_addc_u32 s17, s17, 0
	s_waitcnt lgkmcnt(1)
	v_mfma_f32_32x32x16_bf16 v[50:65], v[74:77], v[70:73], v[50:65]
	ds_read_b128 v[174:177], v106 offset:23104
	ds_read_b128 v[178:181], v107 offset:4672
	global_load_dwordx4 v[74:77], v244, s[76:77] offset:-4096
	s_cmp_eq_u32 s16, 0x38000
	global_load_dwordx4 v[78:81], v244, s[76:77]
	v_mfma_f32_32x32x16_bf16 v[34:49], v[66:69], v[70:73], v[34:49]
	global_load_dwordx4 v[70:73], v242, s[62:63]
	global_load_dwordx4 v[66:69], v243, s[62:63]
	ds_read_b128 v[182:185], v106 offset:18528
	ds_read_b128 v[186:189], v107 offset:96
	s_waitcnt lgkmcnt(4)
	v_mfma_f32_32x32x16_bf16 v[50:65], v[98:101], v[102:105], v[50:65]
	ds_read_b128 v[190:193], v106 offset:23136
	ds_read_b128 v[194:197], v107 offset:4704
	s_waitcnt lgkmcnt(0)
	s_barrier
	v_mfma_f32_32x32x16_bf16 v[34:49], v[174:177], v[102:105], v[34:49]
	v_add_u32_e32 v102, v108, v157
	ds_read_b128 v[106:109], v102 offset:18432
	ds_read_b128 v[110:113], v173
	v_mfma_f32_32x32x16_bf16 v[18:33], v[98:101], v[178:181], v[18:33]
	ds_read_b128 v[102:105], v102 offset:23040
	ds_read_b128 v[98:101], v173 offset:4608
	v_mfma_f32_32x32x16_bf16 v[2:17], v[174:177], v[178:181], v[2:17]
	v_mfma_f32_32x32x16_bf16 v[50:65], v[182:185], v[186:189], v[50:65]
	v_mfma_f32_32x32x16_bf16 v[34:49], v[190:193], v[186:189], v[34:49]
	v_mfma_f32_32x32x16_bf16 v[18:33], v[182:185], v[194:197], v[18:33]
	v_mfma_f32_32x32x16_bf16 v[2:17], v[190:193], v[194:197], v[2:17]
	s_cbranch_scc0 .LBB0_2272
	s_waitcnt lgkmcnt(2)
	v_mfma_f32_32x32x16_bf16 v[50:65], v[106:109], v[110:113], v[50:65]
	s_waitcnt vmcnt(7)
	ds_write_b128 v150, v[90:93] offset:36864
	s_waitcnt vmcnt(6)
	ds_write_b128 v150, v[94:97] offset:55296
	s_lshl_b32 s6, s14, 1
	s_ashr_i32 s7, s6, 31
	s_lshl_b32 s10, s27, 7
	s_lshl_b64 s[6:7], s[6:7], 2
	s_add_u32 s6, s44, s6
	s_waitcnt lgkmcnt(3)
	v_mfma_f32_32x32x16_bf16 v[34:49], v[102:105], v[110:113], v[34:49]
	s_waitcnt vmcnt(5)
	ds_write_b128 v152, v[82:85] offset:36864
	s_waitcnt vmcnt(4)
	ds_write_b128 v152, v[86:89] offset:55296
	s_addc_u32 s7, s45, s7
	s_mov_b32 s16, 0
	s_waitcnt lgkmcnt(4)
	v_mfma_f32_32x32x16_bf16 v[18:33], v[106:109], v[98:101], v[18:33]
	s_waitcnt vmcnt(1)
	ds_write_b128 v154, v[70:73] offset:36864
	ds_write_b128 v154, v[74:77] offset:55296
	v_mfma_f32_32x32x16_bf16 v[2:17], v[102:105], v[98:101], v[2:17]
	s_waitcnt vmcnt(0)
	ds_write_b128 v156, v[66:69] offset:36864
	ds_write_b128 v156, v[78:81] offset:55296
	ds_read_b128 v[66:69], v169 offset:23072
	ds_read_b128 v[70:73], v170 offset:4640
	s_waitcnt lgkmcnt(0)
	v_mfma_f32_32x32x16_bf16 v[2:17], v[66:69], v[70:73], v[2:17]
	ds_read_b128 v[74:77], v169 offset:18464
	ds_read_b128 v[78:81], v169 offset:18496
	s_waitcnt lgkmcnt(1)
	v_mfma_f32_32x32x16_bf16 v[18:33], v[74:77], v[70:73], v[18:33]
	ds_read_b128 v[70:73], v170 offset:32
	ds_read_b128 v[82:85], v170 offset:64
	s_waitcnt lgkmcnt(1)
	v_mfma_f32_32x32x16_bf16 v[50:65], v[74:77], v[70:73], v[50:65]
	ds_read_b128 v[74:77], v169 offset:23104
	ds_read_b128 v[86:89], v170 offset:4672
	v_mfma_f32_32x32x16_bf16 v[34:49], v[66:69], v[70:73], v[34:49]
	ds_read_b128 v[66:69], v169 offset:18528
	ds_read_b128 v[70:73], v170 offset:96
	s_waitcnt lgkmcnt(4)
	v_mfma_f32_32x32x16_bf16 v[50:65], v[78:81], v[82:85], v[50:65]
	ds_read_b128 v[90:93], v169 offset:23136
	ds_read_b128 v[94:97], v170 offset:4704
	s_waitcnt lgkmcnt(0)
	s_barrier
	v_mfma_f32_32x32x16_bf16 v[34:49], v[74:77], v[82:85], v[34:49]
	ds_read_b128 v[82:85], v172 offset:55296
	ds_read_b128 v[98:101], v171 offset:36864
	v_mfma_f32_32x32x16_bf16 v[18:33], v[78:81], v[86:89], v[18:33]
	ds_read_b128 v[78:81], v172 offset:59904
	ds_read_b128 v[102:105], v171 offset:41472
	v_mfma_f32_32x32x16_bf16 v[2:17], v[74:77], v[86:89], v[2:17]
	ds_read_b128 v[74:77], v169 offset:59936
	ds_read_b128 v[86:89], v170 offset:41504
	v_mfma_f32_32x32x16_bf16 v[50:65], v[66:69], v[70:73], v[50:65]
	ds_read_b128 v[106:109], v169 offset:55328
	ds_read_b128 v[110:113], v169 offset:55360
	v_mfma_f32_32x32x16_bf16 v[34:49], v[90:93], v[70:73], v[34:49]
	ds_read_b128 v[70:73], v170 offset:36896
	ds_read_b128 v[138:141], v170 offset:36928
	v_mfma_f32_32x32x16_bf16 v[18:33], v[66:69], v[94:97], v[18:33]
	ds_read_b128 v[66:69], v169 offset:59968
	ds_read_b128 v[142:145], v170 offset:41536
	v_mfma_f32_32x32x16_bf16 v[2:17], v[90:93], v[94:97], v[2:17]
	ds_read_b128 v[90:93], v169 offset:55392
	ds_read_b128 v[94:97], v170 offset:36960
	s_waitcnt lgkmcnt(12)
	v_mfma_f32_32x32x16_bf16 v[50:65], v[82:85], v[98:101], v[50:65]
	ds_read_b128 v[174:177], v169 offset:60000
	ds_read_b128 v[178:181], v170 offset:41568
	s_waitcnt lgkmcnt(0)
	s_barrier
	s_barrier
	v_mfma_f32_32x32x16_bf16 v[34:49], v[78:81], v[98:101], v[34:49]
	v_mfma_f32_32x32x16_bf16 v[18:33], v[82:85], v[102:105], v[18:33]
	v_mfma_f32_32x32x16_bf16 v[2:17], v[78:81], v[102:105], v[2:17]
	v_mfma_f32_32x32x16_bf16 v[50:65], v[106:109], v[70:73], v[50:65]
	v_mfma_f32_32x32x16_bf16 v[34:49], v[74:77], v[70:73], v[34:49]
	v_mfma_f32_32x32x16_bf16 v[18:33], v[106:109], v[86:89], v[18:33]
	v_mfma_f32_32x32x16_bf16 v[2:17], v[74:77], v[86:89], v[2:17]
	v_mfma_f32_32x32x16_bf16 v[50:65], v[110:113], v[138:141], v[50:65]
	v_mfma_f32_32x32x16_bf16 v[34:49], v[66:69], v[138:141], v[34:49]
	v_mfma_f32_32x32x16_bf16 v[18:33], v[110:113], v[142:145], v[18:33]
	v_mfma_f32_32x32x16_bf16 v[2:17], v[66:69], v[142:145], v[2:17]
	v_mfma_f32_32x32x16_bf16 v[50:65], v[90:93], v[94:97], v[50:65]
	s_nop 11
	ds_write_b128 v160, v[50:53]
	ds_write_b128 v160, v[54:57] offset:32
	v_mfma_f32_32x32x16_bf16 v[34:49], v[174:177], v[94:97], v[34:49]
	ds_write_b128 v160, v[58:61] offset:64
	ds_write_b128 v160, v[62:65] offset:96
	v_mfma_f32_32x32x16_bf16 v[18:33], v[90:93], v[178:181], v[18:33]
	s_nop 8
	ds_write_b128 v160, v[34:37] offset:128
	ds_write_b128 v160, v[38:41] offset:160
	v_mfma_f32_32x32x16_bf16 v[2:17], v[174:177], v[178:181], v[2:17]
	ds_write_b128 v160, v[42:45] offset:192
	ds_write_b128 v160, v[46:49] offset:224
	ds_write_b128 v160, v[18:21] offset:16896
	ds_write_b128 v160, v[22:25] offset:16928
	ds_write_b128 v160, v[26:29] offset:16960
	ds_write_b128 v160, v[30:33] offset:16992
	v_or_b32_e32 v20, s10, v1
	s_nop 4
	ds_write_b128 v160, v[2:5] offset:17024
	v_lshl_or_b32 v2, s14, 7, v161
	v_ashrrev_i32_e32 v21, 6, v2
	v_lshl_add_u32 v2, s27, 4, v21
	v_ashrrev_i32_e32 v3, 31, v2
	v_lshlrev_b64 v[2:3], 14, v[2:3]
	v_lshl_add_u64 v[2:3], s[92:93], 0, v[2:3]
	v_lshl_add_u64 v[4:5], v[2:3], 0, v[114:115]
	s_mov_b64 s[14:15], -1
	ds_write_b128 v160, v[6:9] offset:17056
	ds_write_b128 v160, v[10:13] offset:17088
	ds_write_b128 v160, v[14:17] offset:17120
	s_waitcnt lgkmcnt(0)
	s_barrier
	s_branch .LBB0_2275
